# attention loop trims: merged lgkmcnt waits, DMA wait-state filled by base advance, redundant s_cmp removed
# baseline (speedup 1.0000x reference)
; #define AT_LOAD(K0, K1, V0, V1, T) do { const size_t e_ = (size_t)(128 * (T) + sr) * 64 + sc; \
;         K0 = *(const bf16x8*)(kcp + e_); V0 = *(const bf16x8*)(vcp + e_); K1 = *(const bf16x8*)(kcp + e_ + 64 * 64); V1 = *(const bf16x8*)(vcp + e_ + 64 * 64); } while (0)
; #define AT_STORE(K0, K1, V0, V1, BUF) do { *(LAS bf16x8*)(lds + AT_K + (BUF) * AT_KB + kst0) = K0; *(LAS bf16x8*)(lds + AT_K + (BUF) * AT_KB + kst1) = K1; \
;         *(LAS bf16x8*)(lds + AT_V + (BUF) * AT_VB + vst0) = V0; *(LAS bf16x8*)(lds + AT_V + (BUF) * AT_VB + vst1) = V1; } while (0)
; template <int VAR>
; __device__ __forceinline__ void attn_unit(const Args& a, int l, int b, int h, int qrow0  , bool ctxu, const bf16* Z, bf16* Y, LAS unsigned char* lds) {
;     ...
;     AT_LOAD(ka0, ka1, va0, va1, 0); AT_LOAD(kb0, kb1, vb0_, vb1_, 1); AT_STORE(ka0, ka1, va0, va1, 0);
.Lat_noprio:
	s_waitcnt lgkmcnt(0)
	s_add_u32 m0, s51, 0x0
	s_nop 0
	global_load_lds_dwordx4 v158, s[36:37]
	s_add_u32 m0, s51, 0x2000
	s_nop 0
	global_load_lds_dwordx4 v159, s[36:37]
	s_add_u32 m0, s51, 0xc000
	s_add_u32 s36, s36, 0x4000
	s_addc_u32 s37, s37, 0
	global_load_lds_dwordx4 v160, s[48:49]
	s_add_u32 m0, s51, 0xe000
	s_nop 0
	global_load_lds_dwordx4 v161, s[48:49]
	s_add_u32 s48, s48, 0x4000
	s_addc_u32 s49, s49, 0
	s_add_u32 m0, s51, 0x4000
	s_nop 0
	global_load_lds_dwordx4 v158, s[36:37]
	s_add_u32 m0, s51, 0x6000
	s_nop 0
	global_load_lds_dwordx4 v159, s[36:37]
	s_add_u32 m0, s51, 0x10000
	s_add_u32 s36, s36, 0x4000
	s_addc_u32 s37, s37, 0
	global_load_lds_dwordx4 v160, s[48:49]
	s_add_u32 m0, s51, 0x12000
	s_nop 0
	global_load_lds_dwordx4 v161, s[48:49]
	s_add_u32 s48, s48, 0x4000
	s_addc_u32 s49, s49, 0
	s_waitcnt vmcnt(4)
	s_barrier
	s_add_u32 m0, s51, 0x8000
	s_nop 0
	global_load_lds_dwordx4 v158, s[36:37]
	s_add_u32 m0, s51, 0xa000
	s_nop 0
	global_load_lds_dwordx4 v159, s[36:37]
	s_add_u32 m0, s51, 0x14000
	s_add_u32 s36, s36, 0x4000
	s_addc_u32 s37, s37, 0
	global_load_lds_dwordx4 v160, s[48:49]
	s_add_u32 m0, s51, 0x16000
	s_nop 0
	global_load_lds_dwordx4 v161, s[48:49]
	s_add_u32 s48, s48, 0x4000
	s_addc_u32 s49, s49, 0
	ds_read_b128 v[48:51], v144 offset:0
	ds_read_b128 v[52:55], v145 offset:0
	ds_read_b128 v[56:59], v144 offset:4096
	ds_read_b128 v[60:63], v145 offset:4096

.Lat_backg0a:
	v_exp_f32_e32 v96, v96
	v_exp_f32_e32 v97, v97
	v_exp_f32_e32 v98, v98
	v_exp_f32_e32 v99, v99
	v_exp_f32_e32 v100, v100
	v_exp_f32_e32 v101, v101
	v_exp_f32_e32 v102, v102
	v_exp_f32_e32 v103, v103
	v_cvt_pk_bf16_f32 v162, v96, v97
	v_cvt_pk_bf16_f32 v163, v98, v99
	v_cvt_pk_bf16_f32 v164, v100, v101
	v_cvt_pk_bf16_f32 v165, v102, v103
	v_pk_add_f32 v[128:129], v[128:129], v[96:97]
	v_pk_add_f32 v[128:129], v[128:129], v[98:99]
	v_pk_add_f32 v[128:129], v[128:129], v[100:101]
	v_pk_add_f32 v[128:129], v[128:129], v[102:103]
	s_waitcnt lgkmcnt(8)
	v_mfma_f32_32x32x16_bf16 v[0:15], v[162:165], v[168:171], v[0:15]
	v_exp_f32_e32 v104, v104
	v_exp_f32_e32 v105, v105
	v_exp_f32_e32 v106, v106
	v_exp_f32_e32 v107, v107
	v_mfma_f32_32x32x16_bf16 v[16:31], v[162:165], v[172:175], v[16:31]
	v_exp_f32_e32 v108, v108
	v_exp_f32_e32 v109, v109
	v_exp_f32_e32 v110, v110
	v_exp_f32_e32 v111, v111
	v_cvt_pk_bf16_f32 v162, v104, v105
	v_cvt_pk_bf16_f32 v163, v106, v107
	v_cvt_pk_bf16_f32 v164, v108, v109
	v_cvt_pk_bf16_f32 v165, v110, v111
	v_pk_add_f32 v[128:129], v[128:129], v[104:105]
	v_pk_add_f32 v[128:129], v[128:129], v[106:107]
	v_pk_add_f32 v[128:129], v[128:129], v[108:109]
	v_pk_add_f32 v[128:129], v[128:129], v[110:111]
	v_mfma_f32_32x32x16_bf16 v[0:15], v[162:165], v[176:179], v[0:15]
	v_exp_f32_e32 v112, v112
	v_exp_f32_e32 v113, v113
	v_exp_f32_e32 v114, v114
	v_exp_f32_e32 v115, v115
	v_mfma_f32_32x32x16_bf16 v[16:31], v[162:165], v[180:183], v[16:31]
	v_mfma_f32_32x32x16_bf16 v[96:111], v[48:51], v[150:153], v[64:79]
	v_exp_f32_e32 v116, v116
	v_exp_f32_e32 v117, v117
	v_exp_f32_e32 v118, v118
	v_exp_f32_e32 v119, v119
	v_mfma_f32_32x32x16_bf16 v[96:111], v[52:55], v[154:157], v[96:111]
	v_cvt_pk_bf16_f32 v162, v112, v113
	v_cvt_pk_bf16_f32 v163, v114, v115
	v_cvt_pk_bf16_f32 v164, v116, v117
	v_cvt_pk_bf16_f32 v165, v118, v119
	v_pk_add_f32 v[128:129], v[128:129], v[112:113]
	v_pk_add_f32 v[128:129], v[128:129], v[114:115]
	v_pk_add_f32 v[128:129], v[128:129], v[116:117]
	v_pk_add_f32 v[128:129], v[128:129], v[118:119]
	s_waitcnt lgkmcnt(0)
	v_mfma_f32_32x32x16_bf16 v[0:15], v[162:165], v[184:187], v[0:15]
	v_exp_f32_e32 v120, v120
	v_exp_f32_e32 v121, v121
	v_exp_f32_e32 v122, v122
	v_exp_f32_e32 v123, v123
	v_mfma_f32_32x32x16_bf16 v[16:31], v[162:165], v[188:191], v[16:31]
	v_exp_f32_e32 v124, v124
	v_exp_f32_e32 v125, v125
	v_exp_f32_e32 v126, v126
	v_exp_f32_e32 v127, v127
	v_cvt_pk_bf16_f32 v162, v120, v121
	v_cvt_pk_bf16_f32 v163, v122, v123
	v_cvt_pk_bf16_f32 v164, v124, v125
	v_cvt_pk_bf16_f32 v165, v126, v127
	v_pk_add_f32 v[128:129], v[128:129], v[120:121]
	v_pk_add_f32 v[128:129], v[128:129], v[122:123]
	v_pk_add_f32 v[128:129], v[128:129], v[124:125]
	v_pk_add_f32 v[128:129], v[128:129], v[126:127]
	v_mfma_f32_32x32x16_bf16 v[112:127], v[56:59], v[150:153], v[64:79]
	v_mfma_f32_32x32x16_bf16 v[112:127], v[60:63], v[154:157], v[112:127]
	v_mfma_f32_32x32x16_bf16 v[0:15], v[162:165], v[192:195], v[0:15]
	v_max3_f32 v132, v96, v97, v98
	v_max3_f32 v133, v99, v100, v101
	v_max3_f32 v132, v132, v102, v103
	v_max3_f32 v133, v133, v104, v105
	v_max3_f32 v132, v132, v106, v107
	v_max3_f32 v133, v133, v108, v109
	v_max3_f32 v132, v132, v110, v111
	v_mfma_f32_32x32x16_bf16 v[16:31], v[162:165], v[196:199], v[16:31]
	ds_read_b128 v[48:51], v144 offset:8192
	ds_read_b128 v[52:55], v145 offset:8192
	ds_read_b128 v[56:59], v144 offset:12288
	ds_read_b128 v[60:63], v145 offset:12288
	v_max3_f32 v133, v133, v112, v113
	v_max3_f32 v132, v132, v114, v115
	v_max3_f32 v133, v133, v116, v117
	v_max3_f32 v132, v132, v118, v119
	v_max3_f32 v133, v133, v120, v121
	v_max3_f32 v132, v132, v122, v123
	v_max3_f32 v133, v133, v124, v125
	v_max3_f32 v132, v132, v126, v127
	v_max_f32_e32 v132, v132, v133
	s_cmp_lg_u32 s95, 0
	s_cbranch_scc1 .Lat_rareg0b
	v_cmp_lt_f32_e32 vcc, s4, v132
	s_cbranch_vccnz .Lat_rareg0b

; #define AT_LOAD(K0, K1, V0, V1, T) do { const size_t e_ = (size_t)(128 * (T) + sr) * 64 + sc; \
;         K0 = *(const bf16x8*)(kcp + e_); V0 = *(const bf16x8*)(vcp + e_); K1 = *(const bf16x8*)(kcp + e_ + 64 * 64); V1 = *(const bf16x8*)(vcp + e_ + 64 * 64); } while (0)
; #define AT_STORE(K0, K1, V0, V1, BUF) do { *(LAS bf16x8*)(lds + AT_K + (BUF) * AT_KB + kst0) = K0; *(LAS bf16x8*)(lds + AT_K + (BUF) * AT_KB + kst1) = K1; \
;         *(LAS bf16x8*)(lds + AT_V + (BUF) * AT_VB + vst0) = V0; *(LAS bf16x8*)(lds + AT_V + (BUF) * AT_VB + vst1) = V1; } while (0)
; template <int VAR>
; __device__ __forceinline__ void attn_unit(const Args& a, int l, int b, int h, int qrow0  , bool ctxu, const bf16* Z, bf16* Y, LAS unsigned char* lds) {
;     ...
;     for (int t = 0; t < NT; t += 2) {
;         __syncthreads();
;         if (t + 2 < NT) AT_LOAD(ka0, ka1, va0, va1, t + 2);
;         attn_tile(Kb0, vb0, q0, q1, negm, m, o0, o1, lacc, t == 0, wsf, r32, hi);
;         AT_STORE(kb0, kb1, vb0_, vb1_, 1);
;         __syncthreads();
;         if (t + 3 < NT) AT_LOAD(kb0, kb1, vb0_, vb1_, t + 3);
;         attn_tile(Kb0 + AT_KB, vb0 + AT_VB, q0, q1, negm, m, o0, o1, lacc, false, wsf, r32, hi);
;         if (t + 2 < NT) AT_STORE(ka0, ka1, va0, va1, 0);
.Lat_backg1a:
	v_exp_f32_e32 v96, v96
	v_exp_f32_e32 v97, v97
	v_exp_f32_e32 v98, v98
	v_exp_f32_e32 v99, v99
	v_exp_f32_e32 v100, v100
	v_exp_f32_e32 v101, v101
	v_exp_f32_e32 v102, v102
	v_exp_f32_e32 v103, v103
	v_cvt_pk_bf16_f32 v162, v96, v97
	v_cvt_pk_bf16_f32 v163, v98, v99
	v_cvt_pk_bf16_f32 v164, v100, v101
	v_cvt_pk_bf16_f32 v165, v102, v103
	v_pk_add_f32 v[128:129], v[128:129], v[96:97]
	v_pk_add_f32 v[128:129], v[128:129], v[98:99]
	v_pk_add_f32 v[128:129], v[128:129], v[100:101]
	v_pk_add_f32 v[128:129], v[128:129], v[102:103]
	s_waitcnt lgkmcnt(8)
	v_mfma_f32_32x32x16_bf16 v[0:15], v[162:165], v[168:171], v[0:15]
	v_exp_f32_e32 v104, v104
	v_exp_f32_e32 v105, v105
	v_exp_f32_e32 v106, v106
	v_exp_f32_e32 v107, v107
	v_mfma_f32_32x32x16_bf16 v[16:31], v[162:165], v[172:175], v[16:31]
	v_exp_f32_e32 v108, v108
	v_exp_f32_e32 v109, v109
	v_exp_f32_e32 v110, v110
	v_exp_f32_e32 v111, v111
	v_cvt_pk_bf16_f32 v162, v104, v105
	v_cvt_pk_bf16_f32 v163, v106, v107
	v_cvt_pk_bf16_f32 v164, v108, v109
	v_cvt_pk_bf16_f32 v165, v110, v111
	v_pk_add_f32 v[128:129], v[128:129], v[104:105]
	v_pk_add_f32 v[128:129], v[128:129], v[106:107]
	v_pk_add_f32 v[128:129], v[128:129], v[108:109]
	v_pk_add_f32 v[128:129], v[128:129], v[110:111]
	v_mfma_f32_32x32x16_bf16 v[0:15], v[162:165], v[176:179], v[0:15]
	v_exp_f32_e32 v112, v112
	v_exp_f32_e32 v113, v113
	v_exp_f32_e32 v114, v114
	v_exp_f32_e32 v115, v115
	v_mfma_f32_32x32x16_bf16 v[16:31], v[162:165], v[180:183], v[16:31]
	v_mfma_f32_32x32x16_bf16 v[96:111], v[48:51], v[150:153], v[64:79]
	v_exp_f32_e32 v116, v116
	v_exp_f32_e32 v117, v117
	v_exp_f32_e32 v118, v118
	v_exp_f32_e32 v119, v119
	v_mfma_f32_32x32x16_bf16 v[96:111], v[52:55], v[154:157], v[96:111]
	v_cvt_pk_bf16_f32 v162, v112, v113
	v_cvt_pk_bf16_f32 v163, v114, v115
	v_cvt_pk_bf16_f32 v164, v116, v117
	v_cvt_pk_bf16_f32 v165, v118, v119
	v_pk_add_f32 v[128:129], v[128:129], v[112:113]
	v_pk_add_f32 v[128:129], v[128:129], v[114:115]
	v_pk_add_f32 v[128:129], v[128:129], v[116:117]
	v_pk_add_f32 v[128:129], v[128:129], v[118:119]
	s_waitcnt lgkmcnt(0)
	v_mfma_f32_32x32x16_bf16 v[0:15], v[162:165], v[184:187], v[0:15]
	v_exp_f32_e32 v120, v120
	v_exp_f32_e32 v121, v121
	v_exp_f32_e32 v122, v122
	v_exp_f32_e32 v123, v123
	v_mfma_f32_32x32x16_bf16 v[16:31], v[162:165], v[188:191], v[16:31]
	v_exp_f32_e32 v124, v124
	v_exp_f32_e32 v125, v125
	v_exp_f32_e32 v126, v126
	v_exp_f32_e32 v127, v127
	v_cvt_pk_bf16_f32 v162, v120, v121
	v_cvt_pk_bf16_f32 v163, v122, v123
	v_cvt_pk_bf16_f32 v164, v124, v125
	v_cvt_pk_bf16_f32 v165, v126, v127
	v_pk_add_f32 v[128:129], v[128:129], v[120:121]
	v_pk_add_f32 v[128:129], v[128:129], v[122:123]
	v_pk_add_f32 v[128:129], v[128:129], v[124:125]
	v_pk_add_f32 v[128:129], v[128:129], v[126:127]
	v_mfma_f32_32x32x16_bf16 v[112:127], v[56:59], v[150:153], v[64:79]
	v_mfma_f32_32x32x16_bf16 v[112:127], v[60:63], v[154:157], v[112:127]
	v_mfma_f32_32x32x16_bf16 v[0:15], v[162:165], v[192:195], v[0:15]
	v_max3_f32 v132, v96, v97, v98
	v_max3_f32 v133, v99, v100, v101
	v_max3_f32 v132, v132, v102, v103
	v_max3_f32 v133, v133, v104, v105
	v_max3_f32 v132, v132, v106, v107
	v_max3_f32 v133, v133, v108, v109
	v_max3_f32 v132, v132, v110, v111
	v_mfma_f32_32x32x16_bf16 v[16:31], v[162:165], v[196:199], v[16:31]
	s_nop 2
	v_max3_f32 v133, v133, v112, v113
	v_max3_f32 v132, v132, v114, v115
	v_max3_f32 v133, v133, v116, v117
	v_max3_f32 v132, v132, v118, v119
	v_max3_f32 v133, v133, v120, v121
	v_max3_f32 v132, v132, v122, v123
	v_max3_f32 v133, v133, v124, v125
	v_max3_f32 v132, v132, v126, v127
	v_max_f32_e32 v132, v132, v133
	v_cmp_lt_f32_e32 vcc, s4, v132
	s_cbranch_vccnz .Lat_rareg1b
.Lat_backg1b:
	v_exp_f32_e32 v96, v96
	v_exp_f32_e32 v97, v97
	v_exp_f32_e32 v98, v98
	v_exp_f32_e32 v99, v99
	v_exp_f32_e32 v100, v100
	v_exp_f32_e32 v101, v101
	v_exp_f32_e32 v102, v102
	v_exp_f32_e32 v103, v103
	v_cvt_pk_bf16_f32 v162, v96, v97
	v_cvt_pk_bf16_f32 v163, v98, v99
	v_cvt_pk_bf16_f32 v164, v100, v101
	v_cvt_pk_bf16_f32 v165, v102, v103
	v_pk_add_f32 v[130:131], v[130:131], v[96:97]
	v_pk_add_f32 v[130:131], v[130:131], v[98:99]
	v_pk_add_f32 v[130:131], v[130:131], v[100:101]
	v_pk_add_f32 v[130:131], v[130:131], v[102:103]
	v_mfma_f32_32x32x16_bf16 v[80:95], v[162:165], v[168:171], v[80:95]
	v_exp_f32_e32 v104, v104
	v_exp_f32_e32 v105, v105
	v_exp_f32_e32 v106, v106
	v_exp_f32_e32 v107, v107
	v_mfma_f32_32x32x16_bf16 v[200:215], v[162:165], v[172:175], v[200:215]
	v_exp_f32_e32 v108, v108
	v_exp_f32_e32 v109, v109
	v_exp_f32_e32 v110, v110
	v_exp_f32_e32 v111, v111
	v_cvt_pk_bf16_f32 v162, v104, v105
	v_cvt_pk_bf16_f32 v163, v106, v107
	v_cvt_pk_bf16_f32 v164, v108, v109
	v_cvt_pk_bf16_f32 v165, v110, v111
	v_pk_add_f32 v[130:131], v[130:131], v[104:105]
	v_pk_add_f32 v[130:131], v[130:131], v[106:107]
	v_pk_add_f32 v[130:131], v[130:131], v[108:109]
	v_pk_add_f32 v[130:131], v[130:131], v[110:111]
	v_mfma_f32_32x32x16_bf16 v[80:95], v[162:165], v[176:179], v[80:95]
	v_exp_f32_e32 v112, v112
	v_exp_f32_e32 v113, v113
	v_exp_f32_e32 v114, v114
	v_exp_f32_e32 v115, v115
	v_mfma_f32_32x32x16_bf16 v[200:215], v[162:165], v[180:183], v[200:215]
	v_exp_f32_e32 v116, v116
	v_exp_f32_e32 v117, v117
	v_exp_f32_e32 v118, v118
	v_exp_f32_e32 v119, v119
	v_cvt_pk_bf16_f32 v162, v112, v113
	v_cvt_pk_bf16_f32 v163, v114, v115
	v_cvt_pk_bf16_f32 v164, v116, v117
	v_cvt_pk_bf16_f32 v165, v118, v119
	v_pk_add_f32 v[130:131], v[130:131], v[112:113]
	v_pk_add_f32 v[130:131], v[130:131], v[114:115]
	v_pk_add_f32 v[130:131], v[130:131], v[116:117]
	v_pk_add_f32 v[130:131], v[130:131], v[118:119]
	v_mfma_f32_32x32x16_bf16 v[80:95], v[162:165], v[184:187], v[80:95]
	v_exp_f32_e32 v120, v120
	v_exp_f32_e32 v121, v121
	v_exp_f32_e32 v122, v122
	v_exp_f32_e32 v123, v123
	v_mfma_f32_32x32x16_bf16 v[200:215], v[162:165], v[188:191], v[200:215]
	v_exp_f32_e32 v124, v124
	v_exp_f32_e32 v125, v125
	v_exp_f32_e32 v126, v126
	v_exp_f32_e32 v127, v127
	v_cvt_pk_bf16_f32 v162, v120, v121
	v_cvt_pk_bf16_f32 v163, v122, v123
	v_cvt_pk_bf16_f32 v164, v124, v125
	v_cvt_pk_bf16_f32 v165, v126, v127
	v_pk_add_f32 v[130:131], v[130:131], v[120:121]
	v_pk_add_f32 v[130:131], v[130:131], v[122:123]
	v_pk_add_f32 v[130:131], v[130:131], v[124:125]
	v_pk_add_f32 v[130:131], v[130:131], v[126:127]
	s_waitcnt vmcnt(4)
	s_waitcnt lgkmcnt(0)
	s_barrier
	s_cmp_eq_u32 s33, 21
	s_cbranch_scc1 .Lat_ndg1
	s_add_u32 m0, s51, 0x0
	s_nop 0
	global_load_lds_dwordx4 v158, s[36:37]
	s_add_u32 m0, s51, 0x2000
	s_nop 0
	global_load_lds_dwordx4 v159, s[36:37]
	s_add_u32 m0, s51, 0xc000
	s_add_u32 s36, s36, 0x4000
	s_addc_u32 s37, s37, 0
	global_load_lds_dwordx4 v160, s[48:49]
	s_add_u32 m0, s51, 0xe000
	s_nop 0
	global_load_lds_dwordx4 v161, s[48:49]
	s_add_u32 s48, s48, 0x4000
	s_addc_u32 s49, s49, 0

.Lat_backg2a:
	v_exp_f32_e32 v96, v96
	v_exp_f32_e32 v97, v97
	v_exp_f32_e32 v98, v98
	v_exp_f32_e32 v99, v99
	v_exp_f32_e32 v100, v100
	v_exp_f32_e32 v101, v101
	v_exp_f32_e32 v102, v102
	v_exp_f32_e32 v103, v103
	v_cvt_pk_bf16_f32 v162, v96, v97
	v_cvt_pk_bf16_f32 v163, v98, v99
	v_cvt_pk_bf16_f32 v164, v100, v101
	v_cvt_pk_bf16_f32 v165, v102, v103
	v_pk_add_f32 v[128:129], v[128:129], v[96:97]
	v_pk_add_f32 v[128:129], v[128:129], v[98:99]
	v_pk_add_f32 v[128:129], v[128:129], v[100:101]
	v_pk_add_f32 v[128:129], v[128:129], v[102:103]
	s_waitcnt lgkmcnt(8)
	v_mfma_f32_32x32x16_bf16 v[0:15], v[162:165], v[168:171], v[0:15]
	v_exp_f32_e32 v104, v104
	v_exp_f32_e32 v105, v105
	v_exp_f32_e32 v106, v106
	v_exp_f32_e32 v107, v107
	v_mfma_f32_32x32x16_bf16 v[16:31], v[162:165], v[172:175], v[16:31]
	v_exp_f32_e32 v108, v108
	v_exp_f32_e32 v109, v109
	v_exp_f32_e32 v110, v110
	v_exp_f32_e32 v111, v111
	v_cvt_pk_bf16_f32 v162, v104, v105
	v_cvt_pk_bf16_f32 v163, v106, v107
	v_cvt_pk_bf16_f32 v164, v108, v109
	v_cvt_pk_bf16_f32 v165, v110, v111
	v_pk_add_f32 v[128:129], v[128:129], v[104:105]
	v_pk_add_f32 v[128:129], v[128:129], v[106:107]
	v_pk_add_f32 v[128:129], v[128:129], v[108:109]
	v_pk_add_f32 v[128:129], v[128:129], v[110:111]
	v_mfma_f32_32x32x16_bf16 v[0:15], v[162:165], v[176:179], v[0:15]
	v_exp_f32_e32 v112, v112
	v_exp_f32_e32 v113, v113
	v_exp_f32_e32 v114, v114
	v_exp_f32_e32 v115, v115
	v_mfma_f32_32x32x16_bf16 v[16:31], v[162:165], v[180:183], v[16:31]
	v_mfma_f32_32x32x16_bf16 v[96:111], v[48:51], v[150:153], v[64:79]
	v_exp_f32_e32 v116, v116
	v_exp_f32_e32 v117, v117
	v_exp_f32_e32 v118, v118
	v_exp_f32_e32 v119, v119
	v_mfma_f32_32x32x16_bf16 v[96:111], v[52:55], v[154:157], v[96:111]
	v_cvt_pk_bf16_f32 v162, v112, v113
	v_cvt_pk_bf16_f32 v163, v114, v115
	v_cvt_pk_bf16_f32 v164, v116, v117
	v_cvt_pk_bf16_f32 v165, v118, v119
	v_pk_add_f32 v[128:129], v[128:129], v[112:113]
	v_pk_add_f32 v[128:129], v[128:129], v[114:115]
	v_pk_add_f32 v[128:129], v[128:129], v[116:117]
	v_pk_add_f32 v[128:129], v[128:129], v[118:119]
	s_waitcnt lgkmcnt(0)
	v_mfma_f32_32x32x16_bf16 v[0:15], v[162:165], v[184:187], v[0:15]
	v_exp_f32_e32 v120, v120
	v_exp_f32_e32 v121, v121
	v_exp_f32_e32 v122, v122
	v_exp_f32_e32 v123, v123
	v_mfma_f32_32x32x16_bf16 v[16:31], v[162:165], v[188:191], v[16:31]
	v_exp_f32_e32 v124, v124
	v_exp_f32_e32 v125, v125
	v_exp_f32_e32 v126, v126
	v_exp_f32_e32 v127, v127
	v_cvt_pk_bf16_f32 v162, v120, v121
	v_cvt_pk_bf16_f32 v163, v122, v123
	v_cvt_pk_bf16_f32 v164, v124, v125
	v_cvt_pk_bf16_f32 v165, v126, v127
	v_pk_add_f32 v[128:129], v[128:129], v[120:121]
	v_pk_add_f32 v[128:129], v[128:129], v[122:123]
	v_pk_add_f32 v[128:129], v[128:129], v[124:125]
	v_pk_add_f32 v[128:129], v[128:129], v[126:127]
	v_mfma_f32_32x32x16_bf16 v[112:127], v[56:59], v[150:153], v[64:79]
	v_mfma_f32_32x32x16_bf16 v[112:127], v[60:63], v[154:157], v[112:127]
	v_mfma_f32_32x32x16_bf16 v[0:15], v[162:165], v[192:195], v[0:15]
	v_max3_f32 v132, v96, v97, v98
	v_max3_f32 v133, v99, v100, v101
	v_max3_f32 v132, v132, v102, v103
	v_max3_f32 v133, v133, v104, v105
	v_max3_f32 v132, v132, v106, v107
	v_max3_f32 v133, v133, v108, v109
	v_max3_f32 v132, v132, v110, v111
	v_mfma_f32_32x32x16_bf16 v[16:31], v[162:165], v[196:199], v[16:31]
	ds_read_b128 v[48:51], v144 offset:24576
	ds_read_b128 v[52:55], v145 offset:24576
	ds_read_b128 v[56:59], v144 offset:28672
	ds_read_b128 v[60:63], v145 offset:28672
	v_max3_f32 v133, v133, v112, v113
	v_max3_f32 v132, v132, v114, v115
	v_max3_f32 v133, v133, v116, v117
	v_max3_f32 v132, v132, v118, v119
	v_max3_f32 v133, v133, v120, v121
	v_max3_f32 v132, v132, v122, v123
	v_max3_f32 v133, v133, v124, v125
	v_max3_f32 v132, v132, v126, v127
	v_max_f32_e32 v132, v132, v133
	v_cmp_lt_f32_e32 vcc, s4, v132
	s_cbranch_vccnz .Lat_rareg2b

; #define AT_LOAD(K0, K1, V0, V1, T) do { const size_t e_ = (size_t)(128 * (T) + sr) * 64 + sc; \
;         K0 = *(const bf16x8*)(kcp + e_); V0 = *(const bf16x8*)(vcp + e_); K1 = *(const bf16x8*)(kcp + e_ + 64 * 64); V1 = *(const bf16x8*)(vcp + e_ + 64 * 64); } while (0)
; #define AT_STORE(K0, K1, V0, V1, BUF) do { *(LAS bf16x8*)(lds + AT_K + (BUF) * AT_KB + kst0) = K0; *(LAS bf16x8*)(lds + AT_K + (BUF) * AT_KB + kst1) = K1; \
;         *(LAS bf16x8*)(lds + AT_V + (BUF) * AT_VB + vst0) = V0; *(LAS bf16x8*)(lds + AT_V + (BUF) * AT_VB + vst1) = V1; } while (0)
; template <int VAR>
; __device__ __forceinline__ void attn_unit(const Args& a, int l, int b, int h, int qrow0  , bool ctxu, const bf16* Z, bf16* Y, LAS unsigned char* lds) {
;     ...
;     for (int t = 0; t < NT; t += 2) {
;         __syncthreads();
;         if (t + 2 < NT) AT_LOAD(ka0, ka1, va0, va1, t + 2);
;         attn_tile(Kb0, vb0, q0, q1, negm, m, o0, o1, lacc, t == 0, wsf, r32, hi);
;         AT_STORE(kb0, kb1, vb0_, vb1_, 1);
;         __syncthreads();
;         if (t + 3 < NT) AT_LOAD(kb0, kb1, vb0_, vb1_, t + 3);
;         attn_tile(Kb0 + AT_KB, vb0 + AT_VB, q0, q1, negm, m, o0, o1, lacc, false, wsf, r32, hi);
;         if (t + 2 < NT) AT_STORE(ka0, ka1, va0, va1, 0);
.Lat_wdg3:
	s_waitcnt lgkmcnt(0)
	s_barrier
	s_cbranch_scc1 .Lat_ndg3
	s_add_u32 m0, s51, 0x4000
	s_nop 0
	global_load_lds_dwordx4 v158, s[36:37]
	s_add_u32 m0, s51, 0x6000
	s_nop 0
	global_load_lds_dwordx4 v159, s[36:37]
	s_add_u32 m0, s51, 0x10000
	s_add_u32 s36, s36, 0x4000
	s_addc_u32 s37, s37, 0
	global_load_lds_dwordx4 v160, s[48:49]
	s_add_u32 m0, s51, 0x12000
	s_nop 0
	global_load_lds_dwordx4 v161, s[48:49]
	s_add_u32 s48, s48, 0x4000
	s_addc_u32 s49, s49, 0

.Lat_backg4a:
	v_exp_f32_e32 v96, v96
	v_exp_f32_e32 v97, v97
	v_exp_f32_e32 v98, v98
	v_exp_f32_e32 v99, v99
	v_exp_f32_e32 v100, v100
	v_exp_f32_e32 v101, v101
	v_exp_f32_e32 v102, v102
	v_exp_f32_e32 v103, v103
	v_cvt_pk_bf16_f32 v162, v96, v97
	v_cvt_pk_bf16_f32 v163, v98, v99
	v_cvt_pk_bf16_f32 v164, v100, v101
	v_cvt_pk_bf16_f32 v165, v102, v103
	v_pk_add_f32 v[128:129], v[128:129], v[96:97]
	v_pk_add_f32 v[128:129], v[128:129], v[98:99]
	v_pk_add_f32 v[128:129], v[128:129], v[100:101]
	v_pk_add_f32 v[128:129], v[128:129], v[102:103]
	s_waitcnt lgkmcnt(8)
	v_mfma_f32_32x32x16_bf16 v[0:15], v[162:165], v[168:171], v[0:15]
	v_exp_f32_e32 v104, v104
	v_exp_f32_e32 v105, v105
	v_exp_f32_e32 v106, v106
	v_exp_f32_e32 v107, v107
	v_mfma_f32_32x32x16_bf16 v[16:31], v[162:165], v[172:175], v[16:31]
	v_exp_f32_e32 v108, v108
	v_exp_f32_e32 v109, v109
	v_exp_f32_e32 v110, v110
	v_exp_f32_e32 v111, v111
	v_cvt_pk_bf16_f32 v162, v104, v105
	v_cvt_pk_bf16_f32 v163, v106, v107
	v_cvt_pk_bf16_f32 v164, v108, v109
	v_cvt_pk_bf16_f32 v165, v110, v111
	v_pk_add_f32 v[128:129], v[128:129], v[104:105]
	v_pk_add_f32 v[128:129], v[128:129], v[106:107]
	v_pk_add_f32 v[128:129], v[128:129], v[108:109]
	v_pk_add_f32 v[128:129], v[128:129], v[110:111]
	v_mfma_f32_32x32x16_bf16 v[0:15], v[162:165], v[176:179], v[0:15]
	v_exp_f32_e32 v112, v112
	v_exp_f32_e32 v113, v113
	v_exp_f32_e32 v114, v114
	v_exp_f32_e32 v115, v115
	v_mfma_f32_32x32x16_bf16 v[16:31], v[162:165], v[180:183], v[16:31]
	v_mfma_f32_32x32x16_bf16 v[96:111], v[48:51], v[150:153], v[64:79]
	v_exp_f32_e32 v116, v116
	v_exp_f32_e32 v117, v117
	v_exp_f32_e32 v118, v118
	v_exp_f32_e32 v119, v119
	v_mfma_f32_32x32x16_bf16 v[96:111], v[52:55], v[154:157], v[96:111]
	v_cvt_pk_bf16_f32 v162, v112, v113
	v_cvt_pk_bf16_f32 v163, v114, v115
	v_cvt_pk_bf16_f32 v164, v116, v117
	v_cvt_pk_bf16_f32 v165, v118, v119
	v_pk_add_f32 v[128:129], v[128:129], v[112:113]
	v_pk_add_f32 v[128:129], v[128:129], v[114:115]
	v_pk_add_f32 v[128:129], v[128:129], v[116:117]
	v_pk_add_f32 v[128:129], v[128:129], v[118:119]
	s_waitcnt lgkmcnt(0)
	v_mfma_f32_32x32x16_bf16 v[0:15], v[162:165], v[184:187], v[0:15]
	v_exp_f32_e32 v120, v120
	v_exp_f32_e32 v121, v121
	v_exp_f32_e32 v122, v122
	v_exp_f32_e32 v123, v123
	v_mfma_f32_32x32x16_bf16 v[16:31], v[162:165], v[188:191], v[16:31]
	v_exp_f32_e32 v124, v124
	v_exp_f32_e32 v125, v125
	v_exp_f32_e32 v126, v126
	v_exp_f32_e32 v127, v127
	v_cvt_pk_bf16_f32 v162, v120, v121
	v_cvt_pk_bf16_f32 v163, v122, v123
	v_cvt_pk_bf16_f32 v164, v124, v125
	v_cvt_pk_bf16_f32 v165, v126, v127
	v_pk_add_f32 v[128:129], v[128:129], v[120:121]
	v_pk_add_f32 v[128:129], v[128:129], v[122:123]
	v_pk_add_f32 v[128:129], v[128:129], v[124:125]
	v_pk_add_f32 v[128:129], v[128:129], v[126:127]
	v_mfma_f32_32x32x16_bf16 v[112:127], v[56:59], v[150:153], v[64:79]
	v_mfma_f32_32x32x16_bf16 v[112:127], v[60:63], v[154:157], v[112:127]
	v_mfma_f32_32x32x16_bf16 v[0:15], v[162:165], v[192:195], v[0:15]
	v_max3_f32 v132, v96, v97, v98
	v_max3_f32 v133, v99, v100, v101
	v_max3_f32 v132, v132, v102, v103
	v_max3_f32 v133, v133, v104, v105
	v_max3_f32 v132, v132, v106, v107
	v_max3_f32 v133, v133, v108, v109
	v_max3_f32 v132, v132, v110, v111
	v_mfma_f32_32x32x16_bf16 v[16:31], v[162:165], v[196:199], v[16:31]
	ds_read_b128 v[48:51], v144 offset:40960
	ds_read_b128 v[52:55], v145 offset:40960
	ds_read_b128 v[56:59], v144 offset:45056
	ds_read_b128 v[60:63], v145 offset:45056
	v_max3_f32 v133, v133, v112, v113
	v_max3_f32 v132, v132, v114, v115
	v_max3_f32 v133, v133, v116, v117
	v_max3_f32 v132, v132, v118, v119
	v_max3_f32 v133, v133, v120, v121
	v_max3_f32 v132, v132, v122, v123
	v_max3_f32 v133, v133, v124, v125
	v_max3_f32 v132, v132, v126, v127
	v_max_f32_e32 v132, v132, v133
	v_cmp_lt_f32_e32 vcc, s4, v132
	s_cbranch_vccnz .Lat_rareg4b

; #define AT_LOAD(K0, K1, V0, V1, T) do { const size_t e_ = (size_t)(128 * (T) + sr) * 64 + sc; \
;         K0 = *(const bf16x8*)(kcp + e_); V0 = *(const bf16x8*)(vcp + e_); K1 = *(const bf16x8*)(kcp + e_ + 64 * 64); V1 = *(const bf16x8*)(vcp + e_ + 64 * 64); } while (0)
; #define AT_STORE(K0, K1, V0, V1, BUF) do { *(LAS bf16x8*)(lds + AT_K + (BUF) * AT_KB + kst0) = K0; *(LAS bf16x8*)(lds + AT_K + (BUF) * AT_KB + kst1) = K1; \
;         *(LAS bf16x8*)(lds + AT_V + (BUF) * AT_VB + vst0) = V0; *(LAS bf16x8*)(lds + AT_V + (BUF) * AT_VB + vst1) = V1; } while (0)
; template <int VAR>
; __device__ __forceinline__ void attn_unit(const Args& a, int l, int b, int h, int qrow0  , bool ctxu, const bf16* Z, bf16* Y, LAS unsigned char* lds) {
;     ...
;     for (int t = 0; t < NT; t += 2) {
;         __syncthreads();
;         if (t + 2 < NT) AT_LOAD(ka0, ka1, va0, va1, t + 2);
;         attn_tile(Kb0, vb0, q0, q1, negm, m, o0, o1, lacc, t == 0, wsf, r32, hi);
;         AT_STORE(kb0, kb1, vb0_, vb1_, 1);
;         __syncthreads();
;         if (t + 3 < NT) AT_LOAD(kb0, kb1, vb0_, vb1_, t + 3);
;         attn_tile(Kb0 + AT_KB, vb0 + AT_VB, q0, q1, negm, m, o0, o1, lacc, false, wsf, r32, hi);
;         if (t + 2 < NT) AT_STORE(ka0, ka1, va0, va1, 0);
.Lat_wdg5:
	s_waitcnt lgkmcnt(0)
	s_barrier
	s_cbranch_scc1 .Lat_ndg5
	s_add_u32 m0, s51, 0x8000
	s_nop 0
	global_load_lds_dwordx4 v158, s[36:37]
	s_add_u32 m0, s51, 0xa000
	s_nop 0
	global_load_lds_dwordx4 v159, s[36:37]
	s_add_u32 m0, s51, 0x14000
	s_add_u32 s36, s36, 0x4000
	s_addc_u32 s37, s37, 0
	global_load_lds_dwordx4 v160, s[48:49]
	s_add_u32 m0, s51, 0x16000
	s_nop 0
	global_load_lds_dwordx4 v161, s[48:49]
	s_add_u32 s48, s48, 0x4000
	s_addc_u32 s49, s49, 0
